# barrier 3 split: workgroups 0..159 (two ATT0-hosted transposes each) run them right after arriving and poll for the barrier only afterwards; workgroups 160..255 (one item) transpose after attention
# speedup vs baseline: 1.0011x; 1.0011x over previous
.Lnb3_wait:
	v_readlane_b32 s15, v219, 30
	s_nop 1
	s_cmp_lt_u32 s15, 0xa0
	s_cbranch_scc1 .Lnb3_skip
	v_mov_b32_e32 v1, s14
	s_mov_b32 s15, 0

.Lnb3_skip:
.LBB0_326:
	s_or_b64 exec, exec, s[4:5]
	v_readlane_b32 s0, v219, 9
	v_lshlrev_b32_e32 v20, 2, v149
	v_readlane_b32 s8, v219, 17
	v_readlane_b32 s9, v219, 18
	s_waitcnt lgkmcnt(0)
	s_barrier
	s_nop 2
	global_load_dword v0, v20, s[8:9]
	global_load_dword v1, v20, s[8:9] offset:256
	global_load_dword v2, v20, s[8:9] offset:512
	global_load_dword v3, v20, s[8:9] offset:768
	v_mbcnt_hi_u32_b32 v4, -1, v163
	v_and_b32_e32 v5, 64, v4
	v_xor_b32_e32 v6, 32, v4
	v_add_u32_e32 v5, 64, v5
	v_cmp_lt_i32_e32 vcc, v6, v5
	v_xor_b32_e32 v7, 16, v4
	v_xor_b32_e32 v8, 8, v4
	v_cndmask_b32_e32 v6, v4, v6, vcc
	v_lshlrev_b32_e32 v172, 2, v6
	v_cmp_lt_i32_e32 vcc, v7, v5
	v_xor_b32_e32 v9, 4, v4
	v_xor_b32_e32 v10, 2, v4
	v_cndmask_b32_e32 v7, v4, v7, vcc
	v_lshlrev_b32_e32 v173, 2, v7
	v_cmp_lt_i32_e32 vcc, v8, v5
	v_xor_b32_e32 v11, 1, v4
	s_nop 0
	s_cmp_ge_u32 s78, 0xa0
	s_cselect_b64 s[8:9], -1, 0
	v_readlane_b32 s1, v219, 10
	v_readlane_b32 s2, v219, 11
	v_readlane_b32 s3, v219, 12
	v_readlane_b32 s4, v219, 13
	v_readlane_b32 s5, v219, 14
	v_readlane_b32 s6, v219, 15
	v_readlane_b32 s7, v219, 16
	v_readlane_b32 s10, v219, 19
	v_readlane_b32 s11, v219, 20
	v_readlane_b32 s12, v219, 21
	v_readlane_b32 s13, v219, 22
	v_readlane_b32 s14, v219, 23
	v_readlane_b32 s15, v219, 24
	s_waitcnt vmcnt(2)
	v_mul_f32_e32 v6, v0, v1
	ds_bpermute_b32 v6, v172, v6
	s_waitcnt vmcnt(0)
	v_mul_f32_e32 v12, v2, v3
	ds_bpermute_b32 v12, v172, v12
	s_waitcnt lgkmcnt(1)
	v_fmac_f32_e32 v6, v0, v1
	ds_bpermute_b32 v0, v173, v6
	s_waitcnt lgkmcnt(1)
	v_fmac_f32_e32 v12, v2, v3
	ds_bpermute_b32 v1, v173, v12
	v_cndmask_b32_e32 v2, v4, v8, vcc
	v_lshlrev_b32_e32 v174, 2, v2
	s_waitcnt lgkmcnt(1)
	v_add_f32_e32 v0, v6, v0
	ds_bpermute_b32 v2, v174, v0
	s_waitcnt lgkmcnt(1)
	v_add_f32_e32 v1, v12, v1
	ds_bpermute_b32 v3, v174, v1
	v_cmp_lt_i32_e32 vcc, v9, v5
	s_waitcnt lgkmcnt(1)
	v_add_f32_e32 v0, v0, v2
	v_cndmask_b32_e32 v6, v4, v9, vcc
	v_lshlrev_b32_e32 v175, 2, v6
	s_waitcnt lgkmcnt(0)
	v_add_f32_e32 v1, v1, v3
	ds_bpermute_b32 v2, v175, v0
	ds_bpermute_b32 v3, v175, v1
	v_cmp_lt_i32_e32 vcc, v10, v5
	s_waitcnt lgkmcnt(1)
	v_add_f32_e32 v0, v0, v2
	v_cndmask_b32_e32 v6, v4, v10, vcc
	v_lshlrev_b32_e32 v176, 2, v6
	s_waitcnt lgkmcnt(0)
	v_add_f32_e32 v1, v1, v3
	ds_bpermute_b32 v2, v176, v0
	ds_bpermute_b32 v3, v176, v1
	v_cmp_lt_i32_e32 vcc, v11, v5
	s_waitcnt lgkmcnt(1)
	v_add_f32_e32 v21, v0, v2
	v_cndmask_b32_e32 v4, v4, v11, vcc
	v_lshlrev_b32_e32 v177, 2, v4
	s_waitcnt lgkmcnt(0)
	v_add_f32_e32 v22, v1, v3
	ds_bpermute_b32 v23, v177, v21
	ds_bpermute_b32 v24, v177, v22
	s_and_b64 vcc, exec, s[8:9]
	s_cbranch_vccnz .LBB0_347
	s_add_i32 s0, s78, 0xc0
	s_cmpk_gt_i32 s0, 0x25f
	s_waitcnt lgkmcnt(0)
	s_barrier
	s_cbranch_scc1 .LBB0_346
	s_movk_i32 s1, 0x2100
	v_lshrrev_b32_e32 v25, 3, v149
	v_and_b32_e32 v4, 56, v144
	s_cmpk_eq_i32 s58, 0x100
	v_mad_u32_u24 v1, v148, s1, 0
	v_lshrrev_b32_e32 v0, 5, v149
	v_and_b32_e32 v2, 31, v168
	v_mul_u32_u24_e32 v3, 0x84, v4
	v_lshlrev_b32_e32 v7, 2, v25
	s_cselect_b64 s[6:7], -1, 0
	v_mov_b32_e32 v5, 0
	v_lshl_add_u32 v6, v2, 2, v1
	s_movk_i32 s1, 0x84
	v_add3_u32 v26, v1, v3, v7
	v_or_b32_e32 v27, 8, v25
	v_or_b32_e32 v28, 16, v25
	v_or_b32_e32 v29, 24, v25
	v_mov_b32_e32 v1, v0
	s_movk_i32 s2, 0x187f
	s_movk_i32 s3, 0x1ff
	s_movk_i32 s10, 0xcff
	v_lshlrev_b32_e32 v8, 2, v2
	v_lshlrev_b32_e32 v10, 1, v4
	v_mov_b32_e32 v30, 0xffffe780
	v_mov_b32_e32 v31, 0xc00
	v_mov_b32_e32 v32, 0x600
	v_mov_b32_e32 v33, 0x2c0000
	v_mov_b32_e32 v34, 0x1400000
	v_mov_b32_e32 v35, 0x2980000
	v_mov_b32_e32 v36, 0x900000
	v_mov_b32_e32 v37, 0x1e80000
	v_mov_b32_e32 v38, 0x700000
	v_mov_b32_e32 v39, 0x1c80000
	v_mov_b32_e32 v40, 0x100000
	v_mov_b32_e32 v41, 0x1980000
	s_branch .LBB0_330

.LBB0_347:
	v_readlane_b32 s87, v219, 30
	s_nop 1
	s_cmp_ge_u32 s87, 0xa0
	s_cbranch_scc1 .Latt0_dp_skip
	s_mov_b64 s[80:81], exec
	v_readlane_b32 s82, v219, 25
	v_readlane_b32 s83, v219, 26
	s_nop 1
	s_and_b64 s[82:83], s[80:81], s[82:83]
	s_mov_b64 exec, s[82:83]
	s_cbranch_execz .Latt0_dp_join
	v_readlane_b32 s82, v219, 27
	v_readlane_b32 s83, v219, 28
	v_readlane_b32 s84, v219, 29
	s_nop 1
	s_lshl_b32 s84, s84, 8
	s_add_i32 s84, s84, 0x2400
	v_mov_b32_e32 v223, s84
	s_mov_b32 s85, 0
	s_nop 3
.Latt0_dp_spin:
	global_load_dword v221, v223, s[82:83] sc1
	s_waitcnt vmcnt(0)
	v_readfirstlane_b32 s86, v221
	s_nop 1
	s_cmp_ge_u32 s86, 2
	s_cbranch_scc1 .Latt0_dp_join
	s_sleep 1
	s_add_i32 s85, s85, 1
	s_cmp_lt_u32 s85, 0x200000
	s_cbranch_scc1 .Latt0_dp_spin
.Latt0_dp_join:
	s_mov_b64 exec, s[80:81]
	s_barrier
